# adds: residual epilogues (FoX/MLA out-proj, FFN down) issue the second half's residual loads before the first half's stores and atomics, so they no longer retire behind the atomics
# speedup vs baseline: 1.0010x; 1.0010x over previous
.LBB0_577:
	v_lshl_add_u32 v166, s40, 8, v1
	v_lshl_or_b32 v130, s42, 8, v181
	v_ashrrev_i32_e32 v167, 31, v166
	v_ashrrev_i32_e32 v131, 31, v130
	v_lshlrev_b64 v[132:133], 11, v[166:167]
	v_lshl_add_u64 v[132:133], s[16:17], 0, v[132:133]
	v_lshlrev_b64 v[164:165], 1, v[130:131]
	v_lshl_add_u64 v[196:197], v[132:133], 0, v[164:165]
	global_load_dwordx4 v[188:191], v[196:197], off
	global_load_dwordx4 v[192:195], v[196:197], off offset:256
	v_or_b32_e32 v176, 16, v166
	v_or_b32_e32 v172, 32, v166
	v_or_b32_e32 v168, 48, v166
	v_ashrrev_i32_e32 v177, 31, v176
	v_ashrrev_i32_e32 v173, 31, v172
	v_ashrrev_i32_e32 v169, 31, v168
	v_lshlrev_b64 v[130:131], 11, v[176:177]
	v_lshlrev_b64 v[132:133], 11, v[172:173]
	v_lshlrev_b64 v[134:135], 11, v[168:169]
	v_lshl_add_u64 v[130:131], s[16:17], 0, v[130:131]
	v_lshl_add_u64 v[132:133], s[16:17], 0, v[132:133]
	v_lshl_add_u64 v[134:135], s[16:17], 0, v[134:135]
	v_lshl_add_u64 v[178:179], v[130:131], 0, v[164:165]
	v_lshl_add_u64 v[174:175], v[132:133], 0, v[164:165]
	v_lshl_add_u64 v[170:171], v[134:135], 0, v[164:165]
	global_load_dwordx4 v[150:153], v[178:179], off
	global_load_dwordx4 v[146:149], v[178:179], off offset:256
	global_load_dwordx4 v[142:145], v[174:175], off
	global_load_dwordx4 v[138:141], v[174:175], off offset:256
	global_load_dwordx4 v[134:137], v[170:171], off
	global_load_dwordx4 v[130:133], v[170:171], off offset:256
	s_mov_b64 s[98:99], 0x40000
	v_lshl_add_u64 v[234:235], v[196:197], 0, s[98:99]
	global_load_dwordx4 v[210:213], v[234:235], off
	global_load_dwordx4 v[214:217], v[234:235], off offset:256
	v_lshl_add_u64 v[234:235], v[178:179], 0, s[98:99]
	global_load_dwordx4 v[218:221], v[234:235], off
	global_load_dwordx4 v[222:225], v[234:235], off offset:256
	v_lshl_add_u64 v[234:235], v[174:175], 0, s[98:99]
	global_load_dwordx4 v[226:229], v[234:235], off
	global_load_dwordx4 v[230:233], v[234:235], off offset:256
	v_lshl_add_u64 v[234:235], v[170:171], 0, s[98:99]
	global_load_dwordx4 v[238:241], v[234:235], off
	global_load_dwordx4 v[242:245], v[234:235], off offset:256
	v_and_b32_e32 v187, 64, v185
	v_xor_b32_e32 v186, 16, v185
	v_add_u32_e32 v187, 64, v187
	v_xor_b32_e32 v198, 32, v185
	v_cmp_lt_i32_e32 vcc, v186, v187
	s_waitcnt vmcnt(8)
	v_and_b32_e32 v199, 0xffff0000, v188
	v_cndmask_b32_e32 v186, v185, v186, vcc
	v_cmp_lt_i32_e32 vcc, v198, v187
	v_lshlrev_b32_e32 v202, 16, v192
	v_and_b32_e32 v203, 0xffff0000, v192
	v_cndmask_b32_e32 v187, v185, v198, vcc
	v_lshlrev_b32_e32 v198, 16, v188
	v_lshlrev_b32_e32 v188, 16, v189
	v_and_b32_e32 v189, 0xffff0000, v189
	v_lshlrev_b32_e32 v192, 16, v193
	v_and_b32_e32 v193, 0xffff0000, v193
	v_lshlrev_b32_e32 v200, 16, v190
	v_and_b32_e32 v201, 0xffff0000, v190
	v_lshlrev_b32_e32 v190, 16, v191
	v_and_b32_e32 v191, 0xffff0000, v191
	v_lshlrev_b32_e32 v204, 16, v194
	v_and_b32_e32 v205, 0xffff0000, v194
	v_lshlrev_b32_e32 v194, 16, v195
	v_and_b32_e32 v195, 0xffff0000, v195
	v_pk_add_f32 v[128:129], v[128:129], v[188:189]
	v_pk_add_f32 v[126:127], v[126:127], v[198:199]
	v_pk_add_f32 v[120:121], v[120:121], v[192:193]
	v_pk_add_f32 v[118:119], v[118:119], v[202:203]
	v_pk_add_f32 v[124:125], v[124:125], v[190:191]
	v_pk_add_f32 v[122:123], v[122:123], v[200:201]
	v_pk_add_f32 v[188:189], v[116:117], v[194:195]
	v_pk_add_f32 v[190:191], v[114:115], v[204:205]
	v_mul_f32_e32 v116, v127, v127
	v_mul_f32_e32 v117, v129, v129
	v_cvt_pk_bf16_f32 v114, v126, v127
	v_cvt_pk_bf16_f32 v115, v128, v129
	v_mul_f32_e32 v127, v119, v119
	v_mul_f32_e32 v129, v121, v121
	v_mul_f32_e32 v192, v123, v123
	v_mul_f32_e32 v194, v191, v191
	v_fmac_f32_e32 v116, v126, v126
	v_fmac_f32_e32 v117, v128, v128
	v_fmac_f32_e32 v127, v118, v118
	v_fmac_f32_e32 v129, v120, v120
	v_mul_f32_e32 v193, v125, v125
	v_mul_f32_e32 v195, v189, v189
	v_fmac_f32_e32 v192, v122, v122
	v_fmac_f32_e32 v194, v190, v190
	v_add_f32_e32 v116, v116, v117
	v_add_f32_e32 v117, v127, v129
	v_fmac_f32_e32 v193, v124, v124
	v_fmac_f32_e32 v195, v188, v188
	v_add_f32_e32 v116, v192, v116
	v_add_f32_e32 v117, v194, v117
	v_add_f32_e32 v116, v193, v116
	v_add_f32_e32 v117, v195, v117
	v_lshlrev_b32_e32 v186, 2, v186
	v_add_f32_e32 v126, v116, v117
	ds_bpermute_b32 v127, v186, v126
	v_cvt_pk_bf16_f32 v116, v122, v123
	v_cvt_pk_bf16_f32 v117, v124, v125
	global_store_dwordx4 v[196:197], v[114:117], off
	v_cvt_pk_bf16_f32 v118, v118, v119
	v_cvt_pk_bf16_f32 v119, v120, v121
	v_cvt_pk_bf16_f32 v120, v190, v191
	v_cvt_pk_bf16_f32 v121, v188, v189
	global_store_dwordx4 v[196:197], v[118:121], off offset:256
	s_waitcnt lgkmcnt(0)
	v_add_f32_e32 v115, v126, v127
	v_lshlrev_b32_e32 v114, 2, v187
	ds_bpermute_b32 v116, v114, v115
	s_and_saveexec_b64 s[40:41], s[6:7]
	s_cbranch_execz .LBB0_579
	v_lshl_add_u64 v[118:119], v[166:167], 2, s[18:19]
	s_waitcnt lgkmcnt(0)
	v_add_f32_e32 v115, v115, v116
	global_atomic_add_f32 v[118:119], v115, off

.LBB0_585:
	s_or_b64 exec, exec, s[40:41]
	v_add_u32_e32 v102, 0x80, v166
	v_ashrrev_i32_e32 v103, 31, v102
	s_waitcnt lgkmcnt(0)
	v_lshlrev_b64 v[66:67], 11, v[102:103]
	v_lshl_add_u64 v[66:67], s[16:17], 0, v[66:67]
	v_lshl_add_u64 v[112:113], v[66:67], 0, v[164:165]
	s_waitcnt vmcnt(12)
	v_mov_b32_e32 v104, v210
	v_mov_b32_e32 v105, v211
	v_mov_b32_e32 v106, v212
	v_mov_b32_e32 v107, v213
	v_mov_b32_e32 v108, v214
	v_mov_b32_e32 v109, v215
	v_mov_b32_e32 v110, v216
	v_mov_b32_e32 v111, v217
	v_add_u32_e32 v98, 0x90, v166
	v_add_u32_e32 v94, 0xa0, v166
	v_add_u32_e32 v90, 0xb0, v166
	v_ashrrev_i32_e32 v99, 31, v98
	v_ashrrev_i32_e32 v95, 31, v94
	v_ashrrev_i32_e32 v91, 31, v90
	v_lshlrev_b64 v[66:67], 11, v[98:99]
	v_lshlrev_b64 v[68:69], 11, v[94:95]
	v_lshlrev_b64 v[70:71], 11, v[90:91]
	v_lshl_add_u64 v[66:67], s[16:17], 0, v[66:67]
	v_lshl_add_u64 v[68:69], s[16:17], 0, v[68:69]
	v_lshl_add_u64 v[70:71], s[16:17], 0, v[70:71]
	v_lshl_add_u64 v[100:101], v[66:67], 0, v[164:165]
	v_lshl_add_u64 v[96:97], v[68:69], 0, v[164:165]
	v_lshl_add_u64 v[92:93], v[70:71], 0, v[164:165]
	v_mov_b32_e32 v86, v218
	v_mov_b32_e32 v87, v219
	v_mov_b32_e32 v88, v220
	v_mov_b32_e32 v89, v221
	v_mov_b32_e32 v82, v222
	v_mov_b32_e32 v83, v223
	v_mov_b32_e32 v84, v224
	v_mov_b32_e32 v85, v225
	v_mov_b32_e32 v78, v226
	v_mov_b32_e32 v79, v227
	v_mov_b32_e32 v80, v228
	v_mov_b32_e32 v81, v229
	v_mov_b32_e32 v74, v230
	v_mov_b32_e32 v75, v231
	v_mov_b32_e32 v76, v232
	v_mov_b32_e32 v77, v233
	v_mov_b32_e32 v70, v238
	v_mov_b32_e32 v71, v239
	v_mov_b32_e32 v72, v240
	v_mov_b32_e32 v73, v241
	v_mov_b32_e32 v66, v242
	v_mov_b32_e32 v67, v243
	v_mov_b32_e32 v68, v244
	v_mov_b32_e32 v69, v245
	v_lshlrev_b32_e32 v116, 16, v104
	v_and_b32_e32 v117, 0xffff0000, v104
	v_lshlrev_b32_e32 v104, 16, v105
	v_and_b32_e32 v105, 0xffff0000, v105
	v_lshlrev_b32_e32 v120, 16, v108
	v_and_b32_e32 v121, 0xffff0000, v108
	v_lshlrev_b32_e32 v108, 16, v109
	v_and_b32_e32 v109, 0xffff0000, v109
	v_lshlrev_b32_e32 v118, 16, v106
	v_and_b32_e32 v119, 0xffff0000, v106
	v_lshlrev_b32_e32 v106, 16, v107
	v_and_b32_e32 v107, 0xffff0000, v107
	v_lshlrev_b32_e32 v122, 16, v110
	v_and_b32_e32 v123, 0xffff0000, v110
	v_lshlrev_b32_e32 v110, 16, v111
	v_and_b32_e32 v111, 0xffff0000, v111
	v_pk_add_f32 v[64:65], v[64:65], v[104:105]
	v_pk_add_f32 v[62:63], v[62:63], v[116:117]
	v_pk_add_f32 v[56:57], v[56:57], v[108:109]
	v_pk_add_f32 v[54:55], v[54:55], v[120:121]
	v_pk_add_f32 v[60:61], v[60:61], v[106:107]
	v_pk_add_f32 v[58:59], v[58:59], v[118:119]
	v_pk_add_f32 v[104:105], v[52:53], v[110:111]
	v_pk_add_f32 v[106:107], v[50:51], v[122:123]
	v_mul_f32_e32 v52, v63, v63
	v_mul_f32_e32 v53, v65, v65
	v_cvt_pk_bf16_f32 v50, v62, v63
	v_cvt_pk_bf16_f32 v51, v64, v65
	v_mul_f32_e32 v63, v55, v55
	v_mul_f32_e32 v65, v57, v57
	v_mul_f32_e32 v108, v59, v59
	v_mul_f32_e32 v110, v107, v107
	v_fmac_f32_e32 v52, v62, v62
	v_fmac_f32_e32 v53, v64, v64
	v_fmac_f32_e32 v63, v54, v54
	v_fmac_f32_e32 v65, v56, v56
	v_mul_f32_e32 v109, v61, v61
	v_mul_f32_e32 v111, v105, v105
	v_fmac_f32_e32 v108, v58, v58
	v_fmac_f32_e32 v110, v106, v106
	v_add_f32_e32 v52, v52, v53
	v_add_f32_e32 v53, v63, v65
	v_fmac_f32_e32 v109, v60, v60
	v_fmac_f32_e32 v111, v104, v104
	v_add_f32_e32 v52, v108, v52
	v_add_f32_e32 v53, v110, v53
	v_add_f32_e32 v52, v109, v52
	v_add_f32_e32 v53, v111, v53
	v_add_f32_e32 v62, v52, v53
	ds_bpermute_b32 v63, v186, v62
	v_cvt_pk_bf16_f32 v52, v58, v59
	v_cvt_pk_bf16_f32 v53, v60, v61
	global_store_dwordx4 v[112:113], v[50:53], off
	s_waitcnt lgkmcnt(0)
	s_nop 0
	v_add_f32_e32 v50, v62, v63
	ds_bpermute_b32 v51, v114, v50
	v_cvt_pk_bf16_f32 v52, v54, v55
	v_cvt_pk_bf16_f32 v53, v56, v57
	v_cvt_pk_bf16_f32 v54, v106, v107
	v_cvt_pk_bf16_f32 v55, v104, v105
	global_store_dwordx4 v[112:113], v[52:55], off offset:256
	s_and_saveexec_b64 s[40:41], s[6:7]
	s_cbranch_execz .LBB0_587
	v_lshl_add_u64 v[52:53], v[102:103], 2, s[18:19]
	s_waitcnt lgkmcnt(0)
	v_add_f32_e32 v50, v50, v51
	global_atomic_add_f32 v[52:53], v50, off
.LBB0_587:
	s_or_b64 exec, exec, s[40:41]
	v_lshlrev_b32_e32 v50, 16, v86
	s_waitcnt lgkmcnt(0)
	v_and_b32_e32 v51, 0xffff0000, v86
	v_lshlrev_b32_e32 v52, 16, v87
	v_and_b32_e32 v53, 0xffff0000, v87
	v_lshlrev_b32_e32 v54, 16, v88
	v_and_b32_e32 v55, 0xffff0000, v88
	v_lshlrev_b32_e32 v56, 16, v89
	v_and_b32_e32 v57, 0xffff0000, v89
	v_pk_add_f32 v[48:49], v[48:49], v[52:53]
	v_pk_add_f32 v[46:47], v[46:47], v[50:51]
	v_pk_add_f32 v[50:51], v[44:45], v[56:57]
	v_pk_add_f32 v[44:45], v[42:43], v[54:55]
	v_mul_f32_e32 v42, v47, v47
	v_mul_f32_e32 v43, v49, v49
	v_fmac_f32_e32 v42, v46, v46
	v_fmac_f32_e32 v43, v48, v48
	v_add_f32_e32 v42, v42, v43
	v_mul_f32_e32 v43, v45, v45
	v_fmac_f32_e32 v43, v44, v44
	v_lshlrev_b32_e32 v58, 16, v82
	v_and_b32_e32 v59, 0xffff0000, v82
	v_lshlrev_b32_e32 v60, 16, v83
	v_and_b32_e32 v61, 0xffff0000, v83
	v_add_f32_e32 v42, v43, v42
	v_mul_f32_e32 v43, v51, v51
	v_lshlrev_b32_e32 v62, 16, v84
	v_and_b32_e32 v63, 0xffff0000, v84
	v_fmac_f32_e32 v43, v50, v50
	v_pk_add_f32 v[40:41], v[40:41], v[60:61]
	v_pk_add_f32 v[38:39], v[38:39], v[58:59]
	v_add_f32_e32 v52, v43, v42
	v_cvt_pk_bf16_f32 v42, v46, v47
	v_cvt_pk_bf16_f32 v43, v48, v49
	v_pk_add_f32 v[48:49], v[34:35], v[62:63]
	v_mul_f32_e32 v34, v39, v39
	v_mul_f32_e32 v35, v41, v41
	v_fmac_f32_e32 v34, v38, v38
	v_fmac_f32_e32 v35, v40, v40
	v_lshlrev_b32_e32 v64, 16, v85
	v_and_b32_e32 v65, 0xffff0000, v85
	v_add_f32_e32 v34, v34, v35
	v_mul_f32_e32 v35, v49, v49
	v_pk_add_f32 v[46:47], v[36:37], v[64:65]
	v_fmac_f32_e32 v35, v48, v48
	v_add_f32_e32 v34, v35, v34
	v_mul_f32_e32 v35, v47, v47
	v_fmac_f32_e32 v35, v46, v46
	v_add_f32_e32 v34, v35, v34
	v_add_f32_e32 v34, v52, v34
	ds_bpermute_b32 v35, v186, v34
	v_cvt_pk_bf16_f32 v44, v44, v45
	v_cvt_pk_bf16_f32 v45, v50, v51
	global_store_dwordx4 v[100:101], v[42:45], off
	v_cvt_pk_bf16_f32 v36, v38, v39
	s_waitcnt lgkmcnt(0)
	v_add_f32_e32 v34, v34, v35
	ds_bpermute_b32 v35, v114, v34
	v_cvt_pk_bf16_f32 v37, v40, v41
	v_cvt_pk_bf16_f32 v38, v48, v49
	v_cvt_pk_bf16_f32 v39, v46, v47
	global_store_dwordx4 v[100:101], v[36:39], off offset:256
	s_and_saveexec_b64 s[40:41], s[6:7]
	s_cbranch_execz .LBB0_589
	v_lshl_add_u64 v[36:37], v[98:99], 2, s[18:19]
	s_waitcnt lgkmcnt(0)
	v_add_f32_e32 v34, v34, v35
	global_atomic_add_f32 v[36:37], v34, off
.LBB0_589:
	s_or_b64 exec, exec, s[40:41]
	v_lshlrev_b32_e32 v34, 16, v78
	s_waitcnt lgkmcnt(0)
	v_and_b32_e32 v35, 0xffff0000, v78
	v_lshlrev_b32_e32 v36, 16, v79
	v_and_b32_e32 v37, 0xffff0000, v79
	v_lshlrev_b32_e32 v38, 16, v80
	v_and_b32_e32 v39, 0xffff0000, v80
	v_lshlrev_b32_e32 v40, 16, v81
	v_and_b32_e32 v41, 0xffff0000, v81
	v_pk_add_f32 v[32:33], v[32:33], v[36:37]
	v_pk_add_f32 v[30:31], v[30:31], v[34:35]
	v_pk_add_f32 v[34:35], v[28:29], v[40:41]
	v_pk_add_f32 v[28:29], v[26:27], v[38:39]
	v_mul_f32_e32 v26, v31, v31
	v_mul_f32_e32 v27, v33, v33
	v_fmac_f32_e32 v26, v30, v30
	v_fmac_f32_e32 v27, v32, v32
	v_add_f32_e32 v26, v26, v27
	v_mul_f32_e32 v27, v29, v29
	v_fmac_f32_e32 v27, v28, v28
	v_lshlrev_b32_e32 v42, 16, v74
	v_and_b32_e32 v43, 0xffff0000, v74
	v_lshlrev_b32_e32 v44, 16, v75
	v_and_b32_e32 v45, 0xffff0000, v75
	v_add_f32_e32 v26, v27, v26
	v_mul_f32_e32 v27, v35, v35
	v_lshlrev_b32_e32 v46, 16, v76
	v_and_b32_e32 v47, 0xffff0000, v76
	v_fmac_f32_e32 v27, v34, v34
	v_pk_add_f32 v[24:25], v[24:25], v[44:45]
	v_pk_add_f32 v[22:23], v[22:23], v[42:43]
	v_add_f32_e32 v36, v27, v26
	v_cvt_pk_bf16_f32 v26, v30, v31
	v_cvt_pk_bf16_f32 v27, v32, v33
	v_pk_add_f32 v[32:33], v[18:19], v[46:47]
	v_mul_f32_e32 v18, v23, v23
	v_mul_f32_e32 v19, v25, v25
	v_fmac_f32_e32 v18, v22, v22
	v_fmac_f32_e32 v19, v24, v24
	v_lshlrev_b32_e32 v48, 16, v77
	v_and_b32_e32 v49, 0xffff0000, v77
	v_add_f32_e32 v18, v18, v19
	v_mul_f32_e32 v19, v33, v33
	v_pk_add_f32 v[30:31], v[20:21], v[48:49]
	v_fmac_f32_e32 v19, v32, v32
	v_add_f32_e32 v18, v19, v18
	v_mul_f32_e32 v19, v31, v31
	v_fmac_f32_e32 v19, v30, v30
	v_add_f32_e32 v18, v19, v18
	v_add_f32_e32 v18, v36, v18
	ds_bpermute_b32 v19, v186, v18
	v_cvt_pk_bf16_f32 v28, v28, v29
	v_cvt_pk_bf16_f32 v29, v34, v35
	global_store_dwordx4 v[96:97], v[26:29], off
	v_cvt_pk_bf16_f32 v20, v22, v23
	s_waitcnt lgkmcnt(0)
	v_add_f32_e32 v18, v18, v19
	ds_bpermute_b32 v19, v114, v18
	v_cvt_pk_bf16_f32 v21, v24, v25
	v_cvt_pk_bf16_f32 v22, v32, v33
	v_cvt_pk_bf16_f32 v23, v30, v31
	global_store_dwordx4 v[96:97], v[20:23], off offset:256
	s_and_saveexec_b64 s[40:41], s[6:7]
	s_cbranch_execz .LBB0_591
	v_lshl_add_u64 v[20:21], v[94:95], 2, s[18:19]
	s_waitcnt lgkmcnt(0)
	v_add_f32_e32 v18, v18, v19
	global_atomic_add_f32 v[20:21], v18, off
.LBB0_591:
	s_or_b64 exec, exec, s[40:41]
	v_lshlrev_b32_e32 v18, 16, v70
	s_waitcnt lgkmcnt(0)
	v_and_b32_e32 v19, 0xffff0000, v70
	v_lshlrev_b32_e32 v20, 16, v71
	v_and_b32_e32 v21, 0xffff0000, v71
	v_lshlrev_b32_e32 v22, 16, v72
	v_and_b32_e32 v23, 0xffff0000, v72
	v_lshlrev_b32_e32 v24, 16, v73
	v_and_b32_e32 v25, 0xffff0000, v73
	v_pk_add_f32 v[16:17], v[16:17], v[20:21]
	v_pk_add_f32 v[14:15], v[14:15], v[18:19]
	v_pk_add_f32 v[18:19], v[12:13], v[24:25]
	v_pk_add_f32 v[12:13], v[10:11], v[22:23]
	v_mul_f32_e32 v10, v15, v15
	v_mul_f32_e32 v11, v17, v17
	v_fmac_f32_e32 v10, v14, v14
	v_fmac_f32_e32 v11, v16, v16
	v_add_f32_e32 v10, v10, v11
	v_mul_f32_e32 v11, v13, v13
	v_fmac_f32_e32 v11, v12, v12
	v_lshlrev_b32_e32 v26, 16, v66
	v_and_b32_e32 v27, 0xffff0000, v66
	v_lshlrev_b32_e32 v28, 16, v67
	v_and_b32_e32 v29, 0xffff0000, v67
	v_add_f32_e32 v10, v11, v10
	v_mul_f32_e32 v11, v19, v19
	v_lshlrev_b32_e32 v30, 16, v68
	v_and_b32_e32 v31, 0xffff0000, v68
	v_fmac_f32_e32 v11, v18, v18
	v_pk_add_f32 v[8:9], v[8:9], v[28:29]
	v_pk_add_f32 v[6:7], v[6:7], v[26:27]
	v_add_f32_e32 v20, v11, v10
	v_cvt_pk_bf16_f32 v10, v14, v15
	v_cvt_pk_bf16_f32 v11, v16, v17
	v_pk_add_f32 v[16:17], v[2:3], v[30:31]
	v_mul_f32_e32 v2, v7, v7
	v_mul_f32_e32 v3, v9, v9
	v_fmac_f32_e32 v2, v6, v6
	v_fmac_f32_e32 v3, v8, v8
	v_lshlrev_b32_e32 v32, 16, v69
	v_and_b32_e32 v33, 0xffff0000, v69
	v_add_f32_e32 v2, v2, v3
	v_mul_f32_e32 v3, v17, v17
	v_pk_add_f32 v[14:15], v[4:5], v[32:33]
	v_fmac_f32_e32 v3, v16, v16
	v_add_f32_e32 v2, v3, v2
	v_mul_f32_e32 v3, v15, v15
	v_fmac_f32_e32 v3, v14, v14
	v_add_f32_e32 v2, v3, v2
	v_add_f32_e32 v2, v20, v2
	ds_bpermute_b32 v3, v186, v2
	v_cvt_pk_bf16_f32 v12, v12, v13
	v_cvt_pk_bf16_f32 v13, v18, v19
	global_store_dwordx4 v[92:93], v[10:13], off
	v_cvt_pk_bf16_f32 v4, v6, v7
	s_waitcnt lgkmcnt(0)
	v_add_f32_e32 v2, v2, v3
	ds_bpermute_b32 v3, v114, v2
	v_cvt_pk_bf16_f32 v5, v8, v9
	v_cvt_pk_bf16_f32 v6, v16, v17
	v_cvt_pk_bf16_f32 v7, v14, v15
	global_store_dwordx4 v[92:93], v[4:7], off offset:256
	s_and_saveexec_b64 s[40:41], s[6:7]
	s_cbranch_execz .LBB0_593
	v_lshl_add_u64 v[4:5], v[90:91], 2, s[18:19]
	s_waitcnt lgkmcnt(0)
	v_add_f32_e32 v2, v2, v3
	global_atomic_add_f32 v[4:5], v2, off

.LBB0_839:
	v_lshl_add_u32 v166, s38, 8, v1
	v_lshl_or_b32 v130, s40, 8, v181
	v_ashrrev_i32_e32 v167, 31, v166
	v_ashrrev_i32_e32 v131, 31, v130
	v_lshlrev_b64 v[132:133], 11, v[166:167]
	v_lshl_add_u64 v[132:133], s[14:15], 0, v[132:133]
	v_lshlrev_b64 v[164:165], 1, v[130:131]
	v_lshl_add_u64 v[196:197], v[132:133], 0, v[164:165]
	global_load_dwordx4 v[188:191], v[196:197], off
	global_load_dwordx4 v[192:195], v[196:197], off offset:256
	v_or_b32_e32 v176, 16, v166
	v_or_b32_e32 v172, 32, v166
	v_or_b32_e32 v168, 48, v166
	v_ashrrev_i32_e32 v177, 31, v176
	v_ashrrev_i32_e32 v173, 31, v172
	v_ashrrev_i32_e32 v169, 31, v168
	v_lshlrev_b64 v[130:131], 11, v[176:177]
	v_lshlrev_b64 v[132:133], 11, v[172:173]
	v_lshlrev_b64 v[134:135], 11, v[168:169]
	v_lshl_add_u64 v[130:131], s[14:15], 0, v[130:131]
	v_lshl_add_u64 v[132:133], s[14:15], 0, v[132:133]
	v_lshl_add_u64 v[134:135], s[14:15], 0, v[134:135]
	v_lshl_add_u64 v[178:179], v[130:131], 0, v[164:165]
	v_lshl_add_u64 v[174:175], v[132:133], 0, v[164:165]
	v_lshl_add_u64 v[170:171], v[134:135], 0, v[164:165]
	global_load_dwordx4 v[150:153], v[178:179], off
	global_load_dwordx4 v[146:149], v[178:179], off offset:256
	global_load_dwordx4 v[142:145], v[174:175], off
	global_load_dwordx4 v[138:141], v[174:175], off offset:256
	global_load_dwordx4 v[134:137], v[170:171], off
	global_load_dwordx4 v[130:133], v[170:171], off offset:256
	s_mov_b64 s[98:99], 0x40000
	v_lshl_add_u64 v[234:235], v[196:197], 0, s[98:99]
	global_load_dwordx4 v[210:213], v[234:235], off
	global_load_dwordx4 v[214:217], v[234:235], off offset:256
	v_lshl_add_u64 v[234:235], v[178:179], 0, s[98:99]
	global_load_dwordx4 v[218:221], v[234:235], off
	global_load_dwordx4 v[222:225], v[234:235], off offset:256
	v_lshl_add_u64 v[234:235], v[174:175], 0, s[98:99]
	global_load_dwordx4 v[226:229], v[234:235], off
	global_load_dwordx4 v[230:233], v[234:235], off offset:256
	v_lshl_add_u64 v[234:235], v[170:171], 0, s[98:99]
	global_load_dwordx4 v[238:241], v[234:235], off
	global_load_dwordx4 v[242:245], v[234:235], off offset:256
	v_and_b32_e32 v187, 64, v185
	v_xor_b32_e32 v186, 16, v185
	v_add_u32_e32 v187, 64, v187
	v_xor_b32_e32 v198, 32, v185
	v_cmp_lt_i32_e32 vcc, v186, v187
	s_waitcnt vmcnt(8)
	v_and_b32_e32 v199, 0xffff0000, v188
	v_cndmask_b32_e32 v186, v185, v186, vcc
	v_cmp_lt_i32_e32 vcc, v198, v187
	v_lshlrev_b32_e32 v202, 16, v192
	v_and_b32_e32 v203, 0xffff0000, v192
	v_cndmask_b32_e32 v187, v185, v198, vcc
	v_lshlrev_b32_e32 v198, 16, v188
	v_lshlrev_b32_e32 v188, 16, v189
	v_and_b32_e32 v189, 0xffff0000, v189
	v_lshlrev_b32_e32 v192, 16, v193
	v_and_b32_e32 v193, 0xffff0000, v193
	v_lshlrev_b32_e32 v200, 16, v190
	v_and_b32_e32 v201, 0xffff0000, v190
	v_lshlrev_b32_e32 v190, 16, v191
	v_and_b32_e32 v191, 0xffff0000, v191
	v_lshlrev_b32_e32 v204, 16, v194
	v_and_b32_e32 v205, 0xffff0000, v194
	v_lshlrev_b32_e32 v194, 16, v195
	v_and_b32_e32 v195, 0xffff0000, v195
	v_pk_add_f32 v[128:129], v[128:129], v[188:189]
	v_pk_add_f32 v[126:127], v[126:127], v[198:199]
	v_pk_add_f32 v[120:121], v[120:121], v[192:193]
	v_pk_add_f32 v[118:119], v[118:119], v[202:203]
	v_pk_add_f32 v[124:125], v[124:125], v[190:191]
	v_pk_add_f32 v[122:123], v[122:123], v[200:201]
	v_pk_add_f32 v[188:189], v[116:117], v[194:195]
	v_pk_add_f32 v[190:191], v[114:115], v[204:205]
	v_mul_f32_e32 v116, v127, v127
	v_mul_f32_e32 v117, v129, v129
	v_cvt_pk_bf16_f32 v114, v126, v127
	v_cvt_pk_bf16_f32 v115, v128, v129
	v_mul_f32_e32 v127, v119, v119
	v_mul_f32_e32 v129, v121, v121
	v_mul_f32_e32 v192, v123, v123
	v_mul_f32_e32 v194, v191, v191
	v_fmac_f32_e32 v116, v126, v126
	v_fmac_f32_e32 v117, v128, v128
	v_fmac_f32_e32 v127, v118, v118
	v_fmac_f32_e32 v129, v120, v120
	v_mul_f32_e32 v193, v125, v125
	v_mul_f32_e32 v195, v189, v189
	v_fmac_f32_e32 v192, v122, v122
	v_fmac_f32_e32 v194, v190, v190
	v_add_f32_e32 v116, v116, v117
	v_add_f32_e32 v117, v127, v129
	v_fmac_f32_e32 v193, v124, v124
	v_fmac_f32_e32 v195, v188, v188
	v_add_f32_e32 v116, v192, v116
	v_add_f32_e32 v117, v194, v117
	v_add_f32_e32 v116, v193, v116
	v_add_f32_e32 v117, v195, v117
	v_lshlrev_b32_e32 v186, 2, v186
	v_add_f32_e32 v126, v116, v117
	ds_bpermute_b32 v127, v186, v126
	v_cvt_pk_bf16_f32 v116, v122, v123
	v_cvt_pk_bf16_f32 v117, v124, v125
	global_store_dwordx4 v[196:197], v[114:117], off
	v_cvt_pk_bf16_f32 v118, v118, v119
	v_cvt_pk_bf16_f32 v119, v120, v121
	v_cvt_pk_bf16_f32 v120, v190, v191
	v_cvt_pk_bf16_f32 v121, v188, v189
	global_store_dwordx4 v[196:197], v[118:121], off offset:256
	s_waitcnt lgkmcnt(0)
	v_add_f32_e32 v115, v126, v127
	v_lshlrev_b32_e32 v114, 2, v187
	ds_bpermute_b32 v116, v114, v115
	s_and_saveexec_b64 s[38:39], s[6:7]
	s_cbranch_execz .LBB0_841
	v_lshl_add_u64 v[118:119], v[166:167], 2, s[16:17]
	s_waitcnt lgkmcnt(0)
	v_add_f32_e32 v115, v115, v116
	global_atomic_add_f32 v[118:119], v115, off

.LBB0_847:
	s_or_b64 exec, exec, s[38:39]
	v_add_u32_e32 v102, 0x80, v166
	v_ashrrev_i32_e32 v103, 31, v102
	s_waitcnt lgkmcnt(0)
	v_lshlrev_b64 v[66:67], 11, v[102:103]
	v_lshl_add_u64 v[66:67], s[14:15], 0, v[66:67]
	v_lshl_add_u64 v[112:113], v[66:67], 0, v[164:165]
	s_waitcnt vmcnt(12)
	v_mov_b32_e32 v104, v210
	v_mov_b32_e32 v105, v211
	v_mov_b32_e32 v106, v212
	v_mov_b32_e32 v107, v213
	v_mov_b32_e32 v108, v214
	v_mov_b32_e32 v109, v215
	v_mov_b32_e32 v110, v216
	v_mov_b32_e32 v111, v217
	v_add_u32_e32 v98, 0x90, v166
	v_add_u32_e32 v94, 0xa0, v166
	v_add_u32_e32 v90, 0xb0, v166
	v_ashrrev_i32_e32 v99, 31, v98
	v_ashrrev_i32_e32 v95, 31, v94
	v_ashrrev_i32_e32 v91, 31, v90
	v_lshlrev_b64 v[66:67], 11, v[98:99]
	v_lshlrev_b64 v[68:69], 11, v[94:95]
	v_lshlrev_b64 v[70:71], 11, v[90:91]
	v_lshl_add_u64 v[66:67], s[14:15], 0, v[66:67]
	v_lshl_add_u64 v[68:69], s[14:15], 0, v[68:69]
	v_lshl_add_u64 v[70:71], s[14:15], 0, v[70:71]
	v_lshl_add_u64 v[100:101], v[66:67], 0, v[164:165]
	v_lshl_add_u64 v[96:97], v[68:69], 0, v[164:165]
	v_lshl_add_u64 v[92:93], v[70:71], 0, v[164:165]
	v_mov_b32_e32 v86, v218
	v_mov_b32_e32 v87, v219
	v_mov_b32_e32 v88, v220
	v_mov_b32_e32 v89, v221
	v_mov_b32_e32 v82, v222
	v_mov_b32_e32 v83, v223
	v_mov_b32_e32 v84, v224
	v_mov_b32_e32 v85, v225
	v_mov_b32_e32 v78, v226
	v_mov_b32_e32 v79, v227
	v_mov_b32_e32 v80, v228
	v_mov_b32_e32 v81, v229
	v_mov_b32_e32 v74, v230
	v_mov_b32_e32 v75, v231
	v_mov_b32_e32 v76, v232
	v_mov_b32_e32 v77, v233
	v_mov_b32_e32 v70, v238
	v_mov_b32_e32 v71, v239
	v_mov_b32_e32 v72, v240
	v_mov_b32_e32 v73, v241
	v_mov_b32_e32 v66, v242
	v_mov_b32_e32 v67, v243
	v_mov_b32_e32 v68, v244
	v_mov_b32_e32 v69, v245
	v_lshlrev_b32_e32 v116, 16, v104
	v_and_b32_e32 v117, 0xffff0000, v104
	v_lshlrev_b32_e32 v104, 16, v105
	v_and_b32_e32 v105, 0xffff0000, v105
	v_lshlrev_b32_e32 v120, 16, v108
	v_and_b32_e32 v121, 0xffff0000, v108
	v_lshlrev_b32_e32 v108, 16, v109
	v_and_b32_e32 v109, 0xffff0000, v109
	v_lshlrev_b32_e32 v118, 16, v106
	v_and_b32_e32 v119, 0xffff0000, v106
	v_lshlrev_b32_e32 v106, 16, v107
	v_and_b32_e32 v107, 0xffff0000, v107
	v_lshlrev_b32_e32 v122, 16, v110
	v_and_b32_e32 v123, 0xffff0000, v110
	v_lshlrev_b32_e32 v110, 16, v111
	v_and_b32_e32 v111, 0xffff0000, v111
	v_pk_add_f32 v[64:65], v[64:65], v[104:105]
	v_pk_add_f32 v[62:63], v[62:63], v[116:117]
	v_pk_add_f32 v[56:57], v[56:57], v[108:109]
	v_pk_add_f32 v[54:55], v[54:55], v[120:121]
	v_pk_add_f32 v[60:61], v[60:61], v[106:107]
	v_pk_add_f32 v[58:59], v[58:59], v[118:119]
	v_pk_add_f32 v[104:105], v[52:53], v[110:111]
	v_pk_add_f32 v[106:107], v[50:51], v[122:123]
	v_mul_f32_e32 v52, v63, v63
	v_mul_f32_e32 v53, v65, v65
	v_cvt_pk_bf16_f32 v50, v62, v63
	v_cvt_pk_bf16_f32 v51, v64, v65
	v_mul_f32_e32 v63, v55, v55
	v_mul_f32_e32 v65, v57, v57
	v_mul_f32_e32 v108, v59, v59
	v_mul_f32_e32 v110, v107, v107
	v_fmac_f32_e32 v52, v62, v62
	v_fmac_f32_e32 v53, v64, v64
	v_fmac_f32_e32 v63, v54, v54
	v_fmac_f32_e32 v65, v56, v56
	v_mul_f32_e32 v109, v61, v61
	v_mul_f32_e32 v111, v105, v105
	v_fmac_f32_e32 v108, v58, v58
	v_fmac_f32_e32 v110, v106, v106
	v_add_f32_e32 v52, v52, v53
	v_add_f32_e32 v53, v63, v65
	v_fmac_f32_e32 v109, v60, v60
	v_fmac_f32_e32 v111, v104, v104
	v_add_f32_e32 v52, v108, v52
	v_add_f32_e32 v53, v110, v53
	v_add_f32_e32 v52, v109, v52
	v_add_f32_e32 v53, v111, v53
	v_add_f32_e32 v62, v52, v53
	ds_bpermute_b32 v63, v186, v62
	v_cvt_pk_bf16_f32 v52, v58, v59
	v_cvt_pk_bf16_f32 v53, v60, v61
	global_store_dwordx4 v[112:113], v[50:53], off
	s_waitcnt lgkmcnt(0)
	s_nop 0
	v_add_f32_e32 v50, v62, v63
	ds_bpermute_b32 v51, v114, v50
	v_cvt_pk_bf16_f32 v52, v54, v55
	v_cvt_pk_bf16_f32 v53, v56, v57
	v_cvt_pk_bf16_f32 v54, v106, v107
	v_cvt_pk_bf16_f32 v55, v104, v105
	global_store_dwordx4 v[112:113], v[52:55], off offset:256
	s_and_saveexec_b64 s[38:39], s[6:7]
	s_cbranch_execz .LBB0_849
	v_lshl_add_u64 v[52:53], v[102:103], 2, s[16:17]
	s_waitcnt lgkmcnt(0)
	v_add_f32_e32 v50, v50, v51
	global_atomic_add_f32 v[52:53], v50, off
.LBB0_849:
	s_or_b64 exec, exec, s[38:39]
	v_lshlrev_b32_e32 v50, 16, v86
	s_waitcnt lgkmcnt(0)
	v_and_b32_e32 v51, 0xffff0000, v86
	v_lshlrev_b32_e32 v52, 16, v87
	v_and_b32_e32 v53, 0xffff0000, v87
	v_lshlrev_b32_e32 v54, 16, v88
	v_and_b32_e32 v55, 0xffff0000, v88
	v_lshlrev_b32_e32 v56, 16, v89
	v_and_b32_e32 v57, 0xffff0000, v89
	v_pk_add_f32 v[48:49], v[48:49], v[52:53]
	v_pk_add_f32 v[46:47], v[46:47], v[50:51]
	v_pk_add_f32 v[50:51], v[44:45], v[56:57]
	v_pk_add_f32 v[44:45], v[42:43], v[54:55]
	v_mul_f32_e32 v42, v47, v47
	v_mul_f32_e32 v43, v49, v49
	v_fmac_f32_e32 v42, v46, v46
	v_fmac_f32_e32 v43, v48, v48
	v_add_f32_e32 v42, v42, v43
	v_mul_f32_e32 v43, v45, v45
	v_fmac_f32_e32 v43, v44, v44
	v_lshlrev_b32_e32 v58, 16, v82
	v_and_b32_e32 v59, 0xffff0000, v82
	v_lshlrev_b32_e32 v60, 16, v83
	v_and_b32_e32 v61, 0xffff0000, v83
	v_add_f32_e32 v42, v43, v42
	v_mul_f32_e32 v43, v51, v51
	v_lshlrev_b32_e32 v62, 16, v84
	v_and_b32_e32 v63, 0xffff0000, v84
	v_fmac_f32_e32 v43, v50, v50
	v_pk_add_f32 v[40:41], v[40:41], v[60:61]
	v_pk_add_f32 v[38:39], v[38:39], v[58:59]
	v_add_f32_e32 v52, v43, v42
	v_cvt_pk_bf16_f32 v42, v46, v47
	v_cvt_pk_bf16_f32 v43, v48, v49
	v_pk_add_f32 v[48:49], v[34:35], v[62:63]
	v_mul_f32_e32 v34, v39, v39
	v_mul_f32_e32 v35, v41, v41
	v_fmac_f32_e32 v34, v38, v38
	v_fmac_f32_e32 v35, v40, v40
	v_lshlrev_b32_e32 v64, 16, v85
	v_and_b32_e32 v65, 0xffff0000, v85
	v_add_f32_e32 v34, v34, v35
	v_mul_f32_e32 v35, v49, v49
	v_pk_add_f32 v[46:47], v[36:37], v[64:65]
	v_fmac_f32_e32 v35, v48, v48
	v_add_f32_e32 v34, v35, v34
	v_mul_f32_e32 v35, v47, v47
	v_fmac_f32_e32 v35, v46, v46
	v_add_f32_e32 v34, v35, v34
	v_add_f32_e32 v34, v52, v34
	ds_bpermute_b32 v35, v186, v34
	v_cvt_pk_bf16_f32 v44, v44, v45
	v_cvt_pk_bf16_f32 v45, v50, v51
	global_store_dwordx4 v[100:101], v[42:45], off
	v_cvt_pk_bf16_f32 v36, v38, v39
	s_waitcnt lgkmcnt(0)
	v_add_f32_e32 v34, v34, v35
	ds_bpermute_b32 v35, v114, v34
	v_cvt_pk_bf16_f32 v37, v40, v41
	v_cvt_pk_bf16_f32 v38, v48, v49
	v_cvt_pk_bf16_f32 v39, v46, v47
	global_store_dwordx4 v[100:101], v[36:39], off offset:256
	s_and_saveexec_b64 s[38:39], s[6:7]
	s_cbranch_execz .LBB0_851
	v_lshl_add_u64 v[36:37], v[98:99], 2, s[16:17]
	s_waitcnt lgkmcnt(0)
	v_add_f32_e32 v34, v34, v35
	global_atomic_add_f32 v[36:37], v34, off
.LBB0_851:
	s_or_b64 exec, exec, s[38:39]
	v_lshlrev_b32_e32 v34, 16, v78
	s_waitcnt lgkmcnt(0)
	v_and_b32_e32 v35, 0xffff0000, v78
	v_lshlrev_b32_e32 v36, 16, v79
	v_and_b32_e32 v37, 0xffff0000, v79
	v_lshlrev_b32_e32 v38, 16, v80
	v_and_b32_e32 v39, 0xffff0000, v80
	v_lshlrev_b32_e32 v40, 16, v81
	v_and_b32_e32 v41, 0xffff0000, v81
	v_pk_add_f32 v[32:33], v[32:33], v[36:37]
	v_pk_add_f32 v[30:31], v[30:31], v[34:35]
	v_pk_add_f32 v[34:35], v[28:29], v[40:41]
	v_pk_add_f32 v[28:29], v[26:27], v[38:39]
	v_mul_f32_e32 v26, v31, v31
	v_mul_f32_e32 v27, v33, v33
	v_fmac_f32_e32 v26, v30, v30
	v_fmac_f32_e32 v27, v32, v32
	v_add_f32_e32 v26, v26, v27
	v_mul_f32_e32 v27, v29, v29
	v_fmac_f32_e32 v27, v28, v28
	v_lshlrev_b32_e32 v42, 16, v74
	v_and_b32_e32 v43, 0xffff0000, v74
	v_lshlrev_b32_e32 v44, 16, v75
	v_and_b32_e32 v45, 0xffff0000, v75
	v_add_f32_e32 v26, v27, v26
	v_mul_f32_e32 v27, v35, v35
	v_lshlrev_b32_e32 v46, 16, v76
	v_and_b32_e32 v47, 0xffff0000, v76
	v_fmac_f32_e32 v27, v34, v34
	v_pk_add_f32 v[24:25], v[24:25], v[44:45]
	v_pk_add_f32 v[22:23], v[22:23], v[42:43]
	v_add_f32_e32 v36, v27, v26
	v_cvt_pk_bf16_f32 v26, v30, v31
	v_cvt_pk_bf16_f32 v27, v32, v33
	v_pk_add_f32 v[32:33], v[18:19], v[46:47]
	v_mul_f32_e32 v18, v23, v23
	v_mul_f32_e32 v19, v25, v25
	v_fmac_f32_e32 v18, v22, v22
	v_fmac_f32_e32 v19, v24, v24
	v_lshlrev_b32_e32 v48, 16, v77
	v_and_b32_e32 v49, 0xffff0000, v77
	v_add_f32_e32 v18, v18, v19
	v_mul_f32_e32 v19, v33, v33
	v_pk_add_f32 v[30:31], v[20:21], v[48:49]
	v_fmac_f32_e32 v19, v32, v32
	v_add_f32_e32 v18, v19, v18
	v_mul_f32_e32 v19, v31, v31
	v_fmac_f32_e32 v19, v30, v30
	v_add_f32_e32 v18, v19, v18
	v_add_f32_e32 v18, v36, v18
	ds_bpermute_b32 v19, v186, v18
	v_cvt_pk_bf16_f32 v28, v28, v29
	v_cvt_pk_bf16_f32 v29, v34, v35
	global_store_dwordx4 v[96:97], v[26:29], off
	v_cvt_pk_bf16_f32 v20, v22, v23
	s_waitcnt lgkmcnt(0)
	v_add_f32_e32 v18, v18, v19
	ds_bpermute_b32 v19, v114, v18
	v_cvt_pk_bf16_f32 v21, v24, v25
	v_cvt_pk_bf16_f32 v22, v32, v33
	v_cvt_pk_bf16_f32 v23, v30, v31
	global_store_dwordx4 v[96:97], v[20:23], off offset:256
	s_and_saveexec_b64 s[38:39], s[6:7]
	s_cbranch_execz .LBB0_853
	v_lshl_add_u64 v[20:21], v[94:95], 2, s[16:17]
	s_waitcnt lgkmcnt(0)
	v_add_f32_e32 v18, v18, v19
	global_atomic_add_f32 v[20:21], v18, off
.LBB0_853:
	s_or_b64 exec, exec, s[38:39]
	v_lshlrev_b32_e32 v18, 16, v70
	s_waitcnt lgkmcnt(0)
	v_and_b32_e32 v19, 0xffff0000, v70
	v_lshlrev_b32_e32 v20, 16, v71
	v_and_b32_e32 v21, 0xffff0000, v71
	v_lshlrev_b32_e32 v22, 16, v72
	v_and_b32_e32 v23, 0xffff0000, v72
	v_lshlrev_b32_e32 v24, 16, v73
	v_and_b32_e32 v25, 0xffff0000, v73
	v_pk_add_f32 v[16:17], v[16:17], v[20:21]
	v_pk_add_f32 v[14:15], v[14:15], v[18:19]
	v_pk_add_f32 v[18:19], v[12:13], v[24:25]
	v_pk_add_f32 v[12:13], v[10:11], v[22:23]
	v_mul_f32_e32 v10, v15, v15
	v_mul_f32_e32 v11, v17, v17
	v_fmac_f32_e32 v10, v14, v14
	v_fmac_f32_e32 v11, v16, v16
	v_add_f32_e32 v10, v10, v11
	v_mul_f32_e32 v11, v13, v13
	v_fmac_f32_e32 v11, v12, v12
	v_lshlrev_b32_e32 v26, 16, v66
	v_and_b32_e32 v27, 0xffff0000, v66
	v_lshlrev_b32_e32 v28, 16, v67
	v_and_b32_e32 v29, 0xffff0000, v67
	v_add_f32_e32 v10, v11, v10
	v_mul_f32_e32 v11, v19, v19
	v_lshlrev_b32_e32 v30, 16, v68
	v_and_b32_e32 v31, 0xffff0000, v68
	v_fmac_f32_e32 v11, v18, v18
	v_pk_add_f32 v[8:9], v[8:9], v[28:29]
	v_pk_add_f32 v[6:7], v[6:7], v[26:27]
	v_add_f32_e32 v20, v11, v10
	v_cvt_pk_bf16_f32 v10, v14, v15
	v_cvt_pk_bf16_f32 v11, v16, v17
	v_pk_add_f32 v[16:17], v[2:3], v[30:31]
	v_mul_f32_e32 v2, v7, v7
	v_mul_f32_e32 v3, v9, v9
	v_fmac_f32_e32 v2, v6, v6
	v_fmac_f32_e32 v3, v8, v8
	v_lshlrev_b32_e32 v32, 16, v69
	v_and_b32_e32 v33, 0xffff0000, v69
	v_add_f32_e32 v2, v2, v3
	v_mul_f32_e32 v3, v17, v17
	v_pk_add_f32 v[14:15], v[4:5], v[32:33]
	v_fmac_f32_e32 v3, v16, v16
	v_add_f32_e32 v2, v3, v2
	v_mul_f32_e32 v3, v15, v15
	v_fmac_f32_e32 v3, v14, v14
	v_add_f32_e32 v2, v3, v2
	v_add_f32_e32 v2, v20, v2
	ds_bpermute_b32 v3, v186, v2
	v_cvt_pk_bf16_f32 v12, v12, v13
	v_cvt_pk_bf16_f32 v13, v18, v19
	global_store_dwordx4 v[92:93], v[10:13], off
	v_cvt_pk_bf16_f32 v4, v6, v7
	s_waitcnt lgkmcnt(0)
	v_add_f32_e32 v2, v2, v3
	ds_bpermute_b32 v3, v114, v2
	v_cvt_pk_bf16_f32 v5, v8, v9
	v_cvt_pk_bf16_f32 v6, v16, v17
	v_cvt_pk_bf16_f32 v7, v14, v15
	global_store_dwordx4 v[92:93], v[4:7], off offset:256
	s_and_saveexec_b64 s[38:39], s[6:7]
	s_cbranch_execz .LBB0_855
	v_lshl_add_u64 v[4:5], v[90:91], 2, s[16:17]
	s_waitcnt lgkmcnt(0)
	v_add_f32_e32 v2, v2, v3
	global_atomic_add_f32 v[4:5], v2, off

.LBB0_1679:
	v_lshl_add_u32 v168, s34, 8, v183
	v_lshl_or_b32 v128, s36, 8, v185
	v_ashrrev_i32_e32 v169, 31, v168
	v_ashrrev_i32_e32 v129, 31, v128
	v_lshlrev_b64 v[130:131], 11, v[168:169]
	v_lshl_add_u64 v[130:131], s[12:13], 0, v[130:131]
	v_lshlrev_b64 v[166:167], 1, v[128:129]
	v_lshl_add_u64 v[200:201], v[130:131], 0, v[166:167]
	global_load_dwordx4 v[192:195], v[200:201], off
	global_load_dwordx4 v[196:199], v[200:201], off offset:256
	v_or_b32_e32 v178, 16, v168
	v_or_b32_e32 v174, 32, v168
	v_or_b32_e32 v170, 48, v168
	v_ashrrev_i32_e32 v179, 31, v178
	v_ashrrev_i32_e32 v175, 31, v174
	v_ashrrev_i32_e32 v171, 31, v170
	v_lshlrev_b64 v[128:129], 11, v[178:179]
	v_lshlrev_b64 v[130:131], 11, v[174:175]
	v_lshlrev_b64 v[132:133], 11, v[170:171]
	v_lshl_add_u64 v[128:129], s[12:13], 0, v[128:129]
	v_lshl_add_u64 v[130:131], s[12:13], 0, v[130:131]
	v_lshl_add_u64 v[132:133], s[12:13], 0, v[132:133]
	v_lshl_add_u64 v[180:181], v[128:129], 0, v[166:167]
	v_lshl_add_u64 v[176:177], v[130:131], 0, v[166:167]
	v_lshl_add_u64 v[172:173], v[132:133], 0, v[166:167]
	global_load_dwordx4 v[148:151], v[180:181], off
	global_load_dwordx4 v[144:147], v[180:181], off offset:256
	global_load_dwordx4 v[140:143], v[176:177], off
	global_load_dwordx4 v[136:139], v[176:177], off offset:256
	global_load_dwordx4 v[132:135], v[172:173], off
	global_load_dwordx4 v[128:131], v[172:173], off offset:256
	s_mov_b64 s[98:99], 0x40000
	v_lshl_add_u64 v[216:217], v[200:201], 0, s[98:99]
	global_load_dwordx4 v[222:225], v[216:217], off
	global_load_dwordx4 v[226:229], v[216:217], off offset:256
	v_lshl_add_u64 v[216:217], v[180:181], 0, s[98:99]
	global_load_dwordx4 v[230:233], v[216:217], off
	global_load_dwordx4 v[238:241], v[216:217], off offset:256
	v_lshl_add_u64 v[216:217], v[176:177], 0, s[98:99]
	global_load_dwordx4 v[242:245], v[216:217], off
	global_load_dwordx4 v[246:249], v[216:217], off offset:256
	v_lshl_add_u64 v[216:217], v[172:173], 0, s[98:99]
	global_load_dwordx4 v[250:253], v[216:217], off
	v_and_b32_e32 v191, 64, v189
	v_xor_b32_e32 v190, 16, v189
	v_add_u32_e32 v191, 64, v191
	v_xor_b32_e32 v202, 32, v189
	v_cmp_lt_i32_e32 vcc, v190, v191
	s_waitcnt vmcnt(7)
	v_and_b32_e32 v203, 0xffff0000, v192
	v_cndmask_b32_e32 v190, v189, v190, vcc
	v_cmp_lt_i32_e32 vcc, v202, v191
	v_lshlrev_b32_e32 v206, 16, v196
	v_and_b32_e32 v207, 0xffff0000, v196
	v_cndmask_b32_e32 v191, v189, v202, vcc
	v_lshlrev_b32_e32 v202, 16, v192
	v_lshlrev_b32_e32 v192, 16, v193
	v_and_b32_e32 v193, 0xffff0000, v193
	v_lshlrev_b32_e32 v196, 16, v197
	v_and_b32_e32 v197, 0xffff0000, v197
	v_lshlrev_b32_e32 v204, 16, v194
	v_and_b32_e32 v205, 0xffff0000, v194
	v_lshlrev_b32_e32 v194, 16, v195
	v_and_b32_e32 v195, 0xffff0000, v195
	v_lshlrev_b32_e32 v208, 16, v198
	v_and_b32_e32 v209, 0xffff0000, v198
	v_lshlrev_b32_e32 v198, 16, v199
	v_and_b32_e32 v199, 0xffff0000, v199
	v_pk_add_f32 v[126:127], v[126:127], v[192:193]
	v_pk_add_f32 v[124:125], v[124:125], v[202:203]
	v_pk_add_f32 v[118:119], v[118:119], v[196:197]
	v_pk_add_f32 v[116:117], v[116:117], v[206:207]
	v_pk_add_f32 v[122:123], v[122:123], v[194:195]
	v_pk_add_f32 v[120:121], v[120:121], v[204:205]
	v_pk_add_f32 v[192:193], v[114:115], v[198:199]
	v_pk_add_f32 v[194:195], v[112:113], v[208:209]
	v_mul_f32_e32 v114, v125, v125
	v_mul_f32_e32 v115, v127, v127
	v_cvt_pk_bf16_f32 v112, v124, v125
	v_cvt_pk_bf16_f32 v113, v126, v127
	v_mul_f32_e32 v125, v117, v117
	v_mul_f32_e32 v127, v119, v119
	v_mul_f32_e32 v196, v121, v121
	v_mul_f32_e32 v198, v195, v195
	v_fmac_f32_e32 v114, v124, v124
	v_fmac_f32_e32 v115, v126, v126
	v_fmac_f32_e32 v125, v116, v116
	v_fmac_f32_e32 v127, v118, v118
	v_mul_f32_e32 v197, v123, v123
	v_mul_f32_e32 v199, v193, v193
	v_fmac_f32_e32 v196, v120, v120
	v_fmac_f32_e32 v198, v194, v194
	v_add_f32_e32 v114, v114, v115
	v_add_f32_e32 v115, v125, v127
	v_fmac_f32_e32 v197, v122, v122
	v_fmac_f32_e32 v199, v192, v192
	v_add_f32_e32 v114, v196, v114
	v_add_f32_e32 v115, v198, v115
	v_add_f32_e32 v114, v197, v114
	v_add_f32_e32 v115, v199, v115
	v_lshlrev_b32_e32 v190, 2, v190
	v_add_f32_e32 v124, v114, v115
	ds_bpermute_b32 v125, v190, v124
	v_cvt_pk_bf16_f32 v114, v120, v121
	v_cvt_pk_bf16_f32 v115, v122, v123
	global_store_dwordx4 v[200:201], v[112:115], off
	v_cvt_pk_bf16_f32 v116, v116, v117
	v_cvt_pk_bf16_f32 v117, v118, v119
	v_cvt_pk_bf16_f32 v118, v194, v195
	v_cvt_pk_bf16_f32 v119, v192, v193
	global_store_dwordx4 v[200:201], v[116:119], off offset:256
	s_waitcnt lgkmcnt(0)
	v_add_f32_e32 v113, v124, v125
	v_lshlrev_b32_e32 v112, 2, v191
	ds_bpermute_b32 v114, v112, v113
	s_and_saveexec_b64 s[34:35], s[6:7]
	s_cbranch_execz .LBB0_1681
	v_lshl_add_u64 v[116:117], v[168:169], 2, s[14:15]
	s_waitcnt lgkmcnt(0)
	v_add_f32_e32 v113, v113, v114
	global_atomic_add_f32 v[116:117], v113, off

.LBB0_1687:
	s_or_b64 exec, exec, s[34:35]
	v_add_u32_e32 v100, 0x80, v168
	v_ashrrev_i32_e32 v101, 31, v100
	s_waitcnt lgkmcnt(0)
	v_lshlrev_b64 v[64:65], 11, v[100:101]
	v_lshl_add_u64 v[64:65], s[12:13], 0, v[64:65]
	v_lshl_add_u64 v[110:111], v[64:65], 0, v[166:167]
	s_waitcnt vmcnt(12)
	v_mov_b32_e32 v102, v222
	v_mov_b32_e32 v103, v223
	v_mov_b32_e32 v104, v224
	v_mov_b32_e32 v105, v225
	v_mov_b32_e32 v106, v226
	v_mov_b32_e32 v107, v227
	v_mov_b32_e32 v108, v228
	v_mov_b32_e32 v109, v229
	v_add_u32_e32 v96, 0x90, v168
	v_add_u32_e32 v92, 0xa0, v168
	v_add_u32_e32 v88, 0xb0, v168
	v_ashrrev_i32_e32 v97, 31, v96
	v_ashrrev_i32_e32 v93, 31, v92
	v_ashrrev_i32_e32 v89, 31, v88
	v_lshlrev_b64 v[64:65], 11, v[96:97]
	v_lshlrev_b64 v[66:67], 11, v[92:93]
	v_lshlrev_b64 v[68:69], 11, v[88:89]
	v_lshl_add_u64 v[64:65], s[12:13], 0, v[64:65]
	v_lshl_add_u64 v[66:67], s[12:13], 0, v[66:67]
	v_lshl_add_u64 v[68:69], s[12:13], 0, v[68:69]
	v_lshl_add_u64 v[98:99], v[64:65], 0, v[166:167]
	v_lshl_add_u64 v[94:95], v[66:67], 0, v[166:167]
	v_lshl_add_u64 v[90:91], v[68:69], 0, v[166:167]
	v_mov_b32_e32 v84, v230
	v_mov_b32_e32 v85, v231
	v_mov_b32_e32 v86, v232
	v_mov_b32_e32 v87, v233
	v_mov_b32_e32 v80, v238
	v_mov_b32_e32 v81, v239
	v_mov_b32_e32 v82, v240
	v_mov_b32_e32 v83, v241
	v_mov_b32_e32 v76, v242
	v_mov_b32_e32 v77, v243
	v_mov_b32_e32 v78, v244
	v_mov_b32_e32 v79, v245
	v_mov_b32_e32 v72, v246
	v_mov_b32_e32 v73, v247
	v_mov_b32_e32 v74, v248
	v_mov_b32_e32 v75, v249
	v_mov_b32_e32 v68, v250
	v_mov_b32_e32 v69, v251
	v_mov_b32_e32 v70, v252
	v_mov_b32_e32 v71, v253
	global_load_dwordx4 v[64:67], v[90:91], off offset:256
	v_lshlrev_b32_e32 v114, 16, v102
	v_and_b32_e32 v115, 0xffff0000, v102
	v_lshlrev_b32_e32 v102, 16, v103
	v_and_b32_e32 v103, 0xffff0000, v103
	v_lshlrev_b32_e32 v118, 16, v106
	v_and_b32_e32 v119, 0xffff0000, v106
	v_lshlrev_b32_e32 v106, 16, v107
	v_and_b32_e32 v107, 0xffff0000, v107
	v_lshlrev_b32_e32 v116, 16, v104
	v_and_b32_e32 v117, 0xffff0000, v104
	v_lshlrev_b32_e32 v104, 16, v105
	v_and_b32_e32 v105, 0xffff0000, v105
	v_lshlrev_b32_e32 v120, 16, v108
	v_and_b32_e32 v121, 0xffff0000, v108
	v_lshlrev_b32_e32 v108, 16, v109
	v_and_b32_e32 v109, 0xffff0000, v109
	v_pk_add_f32 v[62:63], v[62:63], v[102:103]
	v_pk_add_f32 v[60:61], v[60:61], v[114:115]
	v_pk_add_f32 v[54:55], v[54:55], v[106:107]
	v_pk_add_f32 v[52:53], v[52:53], v[118:119]
	v_pk_add_f32 v[58:59], v[58:59], v[104:105]
	v_pk_add_f32 v[56:57], v[56:57], v[116:117]
	v_pk_add_f32 v[102:103], v[50:51], v[108:109]
	v_pk_add_f32 v[104:105], v[48:49], v[120:121]
	v_mul_f32_e32 v50, v61, v61
	v_mul_f32_e32 v51, v63, v63
	v_cvt_pk_bf16_f32 v48, v60, v61
	v_cvt_pk_bf16_f32 v49, v62, v63
	v_mul_f32_e32 v61, v53, v53
	v_mul_f32_e32 v63, v55, v55
	v_mul_f32_e32 v106, v57, v57
	v_mul_f32_e32 v108, v105, v105
	v_fmac_f32_e32 v50, v60, v60
	v_fmac_f32_e32 v51, v62, v62
	v_fmac_f32_e32 v61, v52, v52
	v_fmac_f32_e32 v63, v54, v54
	v_mul_f32_e32 v107, v59, v59
	v_mul_f32_e32 v109, v103, v103
	v_fmac_f32_e32 v106, v56, v56
	v_fmac_f32_e32 v108, v104, v104
	v_add_f32_e32 v50, v50, v51
	v_add_f32_e32 v51, v61, v63
	v_fmac_f32_e32 v107, v58, v58
	v_fmac_f32_e32 v109, v102, v102
	v_add_f32_e32 v50, v106, v50
	v_add_f32_e32 v51, v108, v51
	v_add_f32_e32 v50, v107, v50
	v_add_f32_e32 v51, v109, v51
	v_add_f32_e32 v60, v50, v51
	ds_bpermute_b32 v61, v190, v60
	v_cvt_pk_bf16_f32 v50, v56, v57
	v_cvt_pk_bf16_f32 v51, v58, v59
	global_store_dwordx4 v[110:111], v[48:51], off
	s_waitcnt lgkmcnt(0)
	s_nop 0
	v_add_f32_e32 v48, v60, v61
	ds_bpermute_b32 v49, v112, v48
	v_cvt_pk_bf16_f32 v50, v52, v53
	v_cvt_pk_bf16_f32 v51, v54, v55
	v_cvt_pk_bf16_f32 v52, v104, v105
	v_cvt_pk_bf16_f32 v53, v102, v103
	global_store_dwordx4 v[110:111], v[50:53], off offset:256
	s_and_saveexec_b64 s[34:35], s[6:7]
	s_cbranch_execz .LBB0_1689
	v_lshl_add_u64 v[50:51], v[100:101], 2, s[14:15]
	s_waitcnt lgkmcnt(0)
	v_add_f32_e32 v48, v48, v49
	global_atomic_add_f32 v[50:51], v48, off
.LBB0_1689:
	s_or_b64 exec, exec, s[34:35]
	v_lshlrev_b32_e32 v48, 16, v84
	s_waitcnt lgkmcnt(0)
	v_and_b32_e32 v49, 0xffff0000, v84
	v_lshlrev_b32_e32 v50, 16, v85
	v_and_b32_e32 v51, 0xffff0000, v85
	v_lshlrev_b32_e32 v52, 16, v86
	v_and_b32_e32 v53, 0xffff0000, v86
	v_lshlrev_b32_e32 v54, 16, v87
	v_and_b32_e32 v55, 0xffff0000, v87
	v_pk_add_f32 v[46:47], v[46:47], v[50:51]
	v_pk_add_f32 v[44:45], v[44:45], v[48:49]
	v_pk_add_f32 v[48:49], v[42:43], v[54:55]
	v_pk_add_f32 v[42:43], v[40:41], v[52:53]
	v_mul_f32_e32 v40, v45, v45
	v_mul_f32_e32 v41, v47, v47
	v_fmac_f32_e32 v40, v44, v44
	v_fmac_f32_e32 v41, v46, v46
	v_add_f32_e32 v40, v40, v41
	v_mul_f32_e32 v41, v43, v43
	v_fmac_f32_e32 v41, v42, v42
	v_lshlrev_b32_e32 v56, 16, v80
	v_and_b32_e32 v57, 0xffff0000, v80
	v_lshlrev_b32_e32 v58, 16, v81
	v_and_b32_e32 v59, 0xffff0000, v81
	v_add_f32_e32 v40, v41, v40
	v_mul_f32_e32 v41, v49, v49
	v_lshlrev_b32_e32 v60, 16, v82
	v_and_b32_e32 v61, 0xffff0000, v82
	v_fmac_f32_e32 v41, v48, v48
	v_pk_add_f32 v[38:39], v[38:39], v[58:59]
	v_pk_add_f32 v[36:37], v[36:37], v[56:57]
	v_add_f32_e32 v50, v41, v40
	v_cvt_pk_bf16_f32 v40, v44, v45
	v_cvt_pk_bf16_f32 v41, v46, v47
	v_pk_add_f32 v[46:47], v[32:33], v[60:61]
	v_mul_f32_e32 v32, v37, v37
	v_mul_f32_e32 v33, v39, v39
	v_fmac_f32_e32 v32, v36, v36
	v_fmac_f32_e32 v33, v38, v38
	v_lshlrev_b32_e32 v62, 16, v83
	v_and_b32_e32 v63, 0xffff0000, v83
	v_add_f32_e32 v32, v32, v33
	v_mul_f32_e32 v33, v47, v47
	v_pk_add_f32 v[44:45], v[34:35], v[62:63]
	v_fmac_f32_e32 v33, v46, v46
	v_add_f32_e32 v32, v33, v32
	v_mul_f32_e32 v33, v45, v45
	v_fmac_f32_e32 v33, v44, v44
	v_add_f32_e32 v32, v33, v32
	v_add_f32_e32 v32, v50, v32
	ds_bpermute_b32 v33, v190, v32
	v_cvt_pk_bf16_f32 v42, v42, v43
	v_cvt_pk_bf16_f32 v43, v48, v49
	global_store_dwordx4 v[98:99], v[40:43], off
	v_cvt_pk_bf16_f32 v34, v36, v37
	s_waitcnt lgkmcnt(0)
	v_add_f32_e32 v32, v32, v33
	ds_bpermute_b32 v33, v112, v32
	v_cvt_pk_bf16_f32 v35, v38, v39
	v_cvt_pk_bf16_f32 v36, v46, v47
	v_cvt_pk_bf16_f32 v37, v44, v45
	global_store_dwordx4 v[98:99], v[34:37], off offset:256
	s_and_saveexec_b64 s[34:35], s[6:7]
	s_cbranch_execz .LBB0_1691
	v_lshl_add_u64 v[34:35], v[96:97], 2, s[14:15]
	s_waitcnt lgkmcnt(0)
	v_add_f32_e32 v32, v32, v33
	global_atomic_add_f32 v[34:35], v32, off
.LBB0_1691:
	s_or_b64 exec, exec, s[34:35]
	v_lshlrev_b32_e32 v32, 16, v76
	s_waitcnt lgkmcnt(0)
	v_and_b32_e32 v33, 0xffff0000, v76
	v_lshlrev_b32_e32 v34, 16, v77
	v_and_b32_e32 v35, 0xffff0000, v77
	v_lshlrev_b32_e32 v36, 16, v78
	v_and_b32_e32 v37, 0xffff0000, v78
	v_lshlrev_b32_e32 v38, 16, v79
	v_and_b32_e32 v39, 0xffff0000, v79
	v_pk_add_f32 v[30:31], v[30:31], v[34:35]
	v_pk_add_f32 v[28:29], v[28:29], v[32:33]
	v_pk_add_f32 v[32:33], v[26:27], v[38:39]
	v_pk_add_f32 v[26:27], v[24:25], v[36:37]
	v_mul_f32_e32 v24, v29, v29
	v_mul_f32_e32 v25, v31, v31
	v_fmac_f32_e32 v24, v28, v28
	v_fmac_f32_e32 v25, v30, v30
	v_add_f32_e32 v24, v24, v25
	v_mul_f32_e32 v25, v27, v27
	v_fmac_f32_e32 v25, v26, v26
	v_lshlrev_b32_e32 v40, 16, v72
	v_and_b32_e32 v41, 0xffff0000, v72
	v_lshlrev_b32_e32 v42, 16, v73
	v_and_b32_e32 v43, 0xffff0000, v73
	v_add_f32_e32 v24, v25, v24
	v_mul_f32_e32 v25, v33, v33
	v_lshlrev_b32_e32 v44, 16, v74
	v_and_b32_e32 v45, 0xffff0000, v74
	v_fmac_f32_e32 v25, v32, v32
	v_pk_add_f32 v[22:23], v[22:23], v[42:43]
	v_pk_add_f32 v[20:21], v[20:21], v[40:41]
	v_add_f32_e32 v34, v25, v24
	v_cvt_pk_bf16_f32 v24, v28, v29
	v_cvt_pk_bf16_f32 v25, v30, v31
	v_pk_add_f32 v[30:31], v[16:17], v[44:45]
	v_mul_f32_e32 v16, v21, v21
	v_mul_f32_e32 v17, v23, v23
	v_fmac_f32_e32 v16, v20, v20
	v_fmac_f32_e32 v17, v22, v22
	v_lshlrev_b32_e32 v46, 16, v75
	v_and_b32_e32 v47, 0xffff0000, v75
	v_add_f32_e32 v16, v16, v17
	v_mul_f32_e32 v17, v31, v31
	v_pk_add_f32 v[28:29], v[18:19], v[46:47]
	v_fmac_f32_e32 v17, v30, v30
	v_add_f32_e32 v16, v17, v16
	v_mul_f32_e32 v17, v29, v29
	v_fmac_f32_e32 v17, v28, v28
	v_add_f32_e32 v16, v17, v16
	v_add_f32_e32 v16, v34, v16
	ds_bpermute_b32 v17, v190, v16
	v_cvt_pk_bf16_f32 v26, v26, v27
	v_cvt_pk_bf16_f32 v27, v32, v33
	global_store_dwordx4 v[94:95], v[24:27], off
	v_cvt_pk_bf16_f32 v18, v20, v21
	s_waitcnt lgkmcnt(0)
	v_add_f32_e32 v16, v16, v17
	ds_bpermute_b32 v17, v112, v16
	v_cvt_pk_bf16_f32 v19, v22, v23
	v_cvt_pk_bf16_f32 v20, v30, v31
	v_cvt_pk_bf16_f32 v21, v28, v29
	global_store_dwordx4 v[94:95], v[18:21], off offset:256
	s_and_saveexec_b64 s[34:35], s[6:7]
	s_cbranch_execz .LBB0_1693
	v_lshl_add_u64 v[18:19], v[92:93], 2, s[14:15]
	s_waitcnt lgkmcnt(0)
	v_add_f32_e32 v16, v16, v17
	global_atomic_add_f32 v[18:19], v16, off
.LBB0_1693:
	s_or_b64 exec, exec, s[34:35]
	v_lshlrev_b32_e32 v16, 16, v68
	s_waitcnt lgkmcnt(0)
	v_and_b32_e32 v17, 0xffff0000, v68
	v_lshlrev_b32_e32 v18, 16, v69
	v_and_b32_e32 v19, 0xffff0000, v69
	v_lshlrev_b32_e32 v20, 16, v70
	v_and_b32_e32 v21, 0xffff0000, v70
	v_lshlrev_b32_e32 v22, 16, v71
	v_and_b32_e32 v23, 0xffff0000, v71
	v_pk_add_f32 v[14:15], v[14:15], v[18:19]
	v_pk_add_f32 v[12:13], v[12:13], v[16:17]
	v_pk_add_f32 v[16:17], v[10:11], v[22:23]
	v_pk_add_f32 v[10:11], v[8:9], v[20:21]
	v_mul_f32_e32 v8, v13, v13
	v_mul_f32_e32 v9, v15, v15
	v_fmac_f32_e32 v8, v12, v12
	v_fmac_f32_e32 v9, v14, v14
	v_add_f32_e32 v8, v8, v9
	v_mul_f32_e32 v9, v11, v11
	v_fmac_f32_e32 v9, v10, v10
	s_waitcnt vmcnt(9)
	v_lshlrev_b32_e32 v24, 16, v64
	v_and_b32_e32 v25, 0xffff0000, v64
	v_lshlrev_b32_e32 v26, 16, v65
	v_and_b32_e32 v27, 0xffff0000, v65
	v_add_f32_e32 v8, v9, v8
	v_mul_f32_e32 v9, v17, v17
	v_lshlrev_b32_e32 v28, 16, v66
	v_and_b32_e32 v29, 0xffff0000, v66
	v_fmac_f32_e32 v9, v16, v16
	v_pk_add_f32 v[6:7], v[6:7], v[26:27]
	v_pk_add_f32 v[4:5], v[4:5], v[24:25]
	v_add_f32_e32 v18, v9, v8
	v_cvt_pk_bf16_f32 v8, v12, v13
	v_cvt_pk_bf16_f32 v9, v14, v15
	v_pk_add_f32 v[14:15], v[0:1], v[28:29]
	v_mul_f32_e32 v0, v5, v5
	v_mul_f32_e32 v1, v7, v7
	v_fmac_f32_e32 v0, v4, v4
	v_fmac_f32_e32 v1, v6, v6
	v_lshlrev_b32_e32 v30, 16, v67
	v_and_b32_e32 v31, 0xffff0000, v67
	v_add_f32_e32 v0, v0, v1
	v_mul_f32_e32 v1, v15, v15
	v_pk_add_f32 v[12:13], v[2:3], v[30:31]
	v_fmac_f32_e32 v1, v14, v14
	v_add_f32_e32 v0, v1, v0
	v_mul_f32_e32 v1, v13, v13
	v_fmac_f32_e32 v1, v12, v12
	v_add_f32_e32 v0, v1, v0
	v_add_f32_e32 v0, v18, v0
	ds_bpermute_b32 v1, v190, v0
	v_cvt_pk_bf16_f32 v10, v10, v11
	v_cvt_pk_bf16_f32 v11, v16, v17
	global_store_dwordx4 v[90:91], v[8:11], off
	v_cvt_pk_bf16_f32 v2, v4, v5
	s_waitcnt lgkmcnt(0)
	v_add_f32_e32 v0, v0, v1
	ds_bpermute_b32 v1, v112, v0
	v_cvt_pk_bf16_f32 v3, v6, v7
	v_cvt_pk_bf16_f32 v4, v14, v15
	v_cvt_pk_bf16_f32 v5, v12, v13
	global_store_dwordx4 v[90:91], v[2:5], off offset:256
	s_and_saveexec_b64 s[34:35], s[6:7]
	s_cbranch_execz .LBB0_1695
	v_lshl_add_u64 v[2:3], v[88:89], 2, s[14:15]
	s_waitcnt lgkmcnt(0)
	v_add_f32_e32 v0, v0, v1
	global_atomic_add_f32 v[2:3], v0, off
